# attention near-tile bias path: packed fp32 adds split into scalar pairs
# speedup vs baseline: 1.0040x; 1.0040x over previous
.Lnear_u1e:
	v_add_u32_e32 v130, s21, v248
	v_add_u32_e32 v130, 0x11f, v130
	v_and_b32_e32 v130, 0x3ffffffc, v130
	v_lshl_add_u32 v166, v130, 2, v0
	ds_read_b128 v[130:133], v166
	ds_read_b128 v[134:137], v166 offset:16
	ds_read_b128 v[138:141], v166 offset:64
	ds_read_b128 v[142:145], v166 offset:80
	s_waitcnt lgkmcnt(0)
	v_add_f32_e32 v84, v84, v132
	v_add_f32_e32 v85, v85, v133
	v_add_f32_e32 v86, v86, v134
	v_add_f32_e32 v87, v87, v135
	v_add_f32_e32 v90, v90, v138
	v_add_f32_e32 v91, v91, v139
	v_add_f32_e32 v94, v94, v142
	v_add_f32_e32 v95, v95, v143
	v_add_f32_e32 v96, v96, v144
	v_add_f32_e32 v97, v97, v145
	v_add_f32_e32 v92, v92, v140
	v_add_f32_e32 v93, v93, v141
	v_add_f32_e32 v88, v88, v136
	v_add_f32_e32 v89, v89, v137
	v_add_f32_e32 v82, v82, v130
	v_add_f32_e32 v83, v83, v131
	ds_read_b128 v[130:133], v166 offset:128
	ds_read_b128 v[134:137], v166 offset:144
	ds_read_b128 v[138:141], v166 offset:192
	ds_read_b128 v[142:145], v166 offset:208
	s_waitcnt lgkmcnt(0)
	v_add_f32_e32 v100, v100, v132
	v_add_f32_e32 v101, v101, v133
	v_add_f32_e32 v102, v102, v134
	v_add_f32_e32 v103, v103, v135
	v_add_f32_e32 v106, v106, v138
	v_add_f32_e32 v107, v107, v139
	v_add_f32_e32 v110, v110, v142
	v_add_f32_e32 v111, v111, v143
	v_add_f32_e32 v112, v112, v144
	v_add_f32_e32 v113, v113, v145
	v_add_f32_e32 v108, v108, v140
	v_add_f32_e32 v109, v109, v141
	v_add_f32_e32 v104, v104, v136
	v_add_f32_e32 v105, v105, v137
	v_add_f32_e32 v98, v98, v130
	v_add_f32_e32 v99, v99, v131
	s_branch .LBB0_188
.Lnear_u1o:
	v_add_u32_e32 v130, s21, v248
	v_add_u32_e32 v130, 0x15f, v130
	v_and_b32_e32 v130, 0x3ffffffc, v130
	v_lshl_add_u32 v162, v130, 2, v0
	ds_read_b128 v[130:133], v162
	ds_read_b128 v[134:137], v162 offset:16
	ds_read_b128 v[138:141], v162 offset:64
	ds_read_b128 v[142:145], v162 offset:80
	s_waitcnt lgkmcnt(0)
	v_add_f32_e32 v84, v84, v132
	v_add_f32_e32 v85, v85, v133
	v_add_f32_e32 v86, v86, v134
	v_add_f32_e32 v87, v87, v135
	v_add_f32_e32 v90, v90, v138
	v_add_f32_e32 v91, v91, v139
	v_add_f32_e32 v94, v94, v142
	v_add_f32_e32 v95, v95, v143
	v_add_f32_e32 v96, v96, v144
	v_add_f32_e32 v97, v97, v145
	v_add_f32_e32 v92, v92, v140
	v_add_f32_e32 v93, v93, v141
	v_add_f32_e32 v88, v88, v136
	v_add_f32_e32 v89, v89, v137
	v_add_f32_e32 v82, v82, v130
	v_add_f32_e32 v83, v83, v131
	ds_read_b128 v[130:133], v162 offset:128
	ds_read_b128 v[134:137], v162 offset:144
	ds_read_b128 v[138:141], v162 offset:192
	ds_read_b128 v[142:145], v162 offset:208
	s_waitcnt lgkmcnt(0)
	v_add_f32_e32 v100, v100, v132
	v_add_f32_e32 v101, v101, v133
	v_add_f32_e32 v102, v102, v134
	v_add_f32_e32 v103, v103, v135
	v_add_f32_e32 v106, v106, v138
	v_add_f32_e32 v107, v107, v139
	v_add_f32_e32 v110, v110, v142
	v_add_f32_e32 v111, v111, v143
	v_add_f32_e32 v112, v112, v144
	v_add_f32_e32 v113, v113, v145
	v_add_f32_e32 v108, v108, v140
	v_add_f32_e32 v109, v109, v141
	v_add_f32_e32 v104, v104, v136
	v_add_f32_e32 v105, v105, v137
	v_add_f32_e32 v98, v98, v130
	v_add_f32_e32 v99, v99, v131
	s_branch .LBB0_228

.Lnear_u2e:
	v_add3_u32 v130, v249, s20, 47
	v_and_b32_e32 v130, 0x3ffffffc, v130
	v_lshl_add_u32 v166, v130, 2, v244
	ds_read_b128 v[130:133], v166
	ds_read_b128 v[134:137], v166 offset:16
	ds_read_b128 v[138:141], v166 offset:64
	ds_read_b128 v[142:145], v166 offset:80
	s_waitcnt lgkmcnt(0)
	v_add_f32_e32 v84, v84, v132
	v_add_f32_e32 v85, v85, v133
	v_add_f32_e32 v88, v88, v136
	v_add_f32_e32 v89, v89, v137
	v_add_f32_e32 v92, v92, v140
	v_add_f32_e32 v93, v93, v141
	v_add_f32_e32 v96, v96, v144
	v_add_f32_e32 v97, v97, v145
	v_add_f32_e32 v94, v94, v142
	v_add_f32_e32 v95, v95, v143
	v_add_f32_e32 v90, v90, v138
	v_add_f32_e32 v91, v91, v139
	v_add_f32_e32 v86, v86, v134
	v_add_f32_e32 v87, v87, v135
	v_add_f32_e32 v82, v82, v130
	v_add_f32_e32 v83, v83, v131
	ds_read_b128 v[130:133], v166 offset:128
	ds_read_b128 v[134:137], v166 offset:144
	ds_read_b128 v[138:141], v166 offset:192
	ds_read_b128 v[142:145], v166 offset:208
	s_waitcnt lgkmcnt(0)
	v_add_f32_e32 v100, v100, v132
	v_add_f32_e32 v101, v101, v133
	v_add_f32_e32 v104, v104, v136
	v_add_f32_e32 v105, v105, v137
	v_add_f32_e32 v108, v108, v140
	v_add_f32_e32 v109, v109, v141
	v_add_f32_e32 v112, v112, v144
	v_add_f32_e32 v113, v113, v145
	v_add_f32_e32 v110, v110, v142
	v_add_f32_e32 v111, v111, v143
	v_add_f32_e32 v106, v106, v138
	v_add_f32_e32 v107, v107, v139
	v_add_f32_e32 v102, v102, v134
	v_add_f32_e32 v103, v103, v135
	v_add_f32_e32 v98, v98, v130
	v_add_f32_e32 v99, v99, v131
	s_branch .LBB0_291
.Lnear_u2o:
	v_add_u32_e32 v130, s20, v249
	v_add_u32_e32 v130, 0x6f, v130
	v_and_b32_e32 v130, 0x3ffffffc, v130
	v_lshl_add_u32 v162, v130, 2, v244
	ds_read_b128 v[130:133], v162
	ds_read_b128 v[134:137], v162 offset:16
	ds_read_b128 v[138:141], v162 offset:64
	ds_read_b128 v[142:145], v162 offset:80
	s_waitcnt lgkmcnt(0)
	v_add_f32_e32 v84, v84, v132
	v_add_f32_e32 v85, v85, v133
	v_add_f32_e32 v86, v86, v134
	v_add_f32_e32 v87, v87, v135
	v_add_f32_e32 v90, v90, v138
	v_add_f32_e32 v91, v91, v139
	v_add_f32_e32 v94, v94, v142
	v_add_f32_e32 v95, v95, v143
	v_add_f32_e32 v96, v96, v144
	v_add_f32_e32 v97, v97, v145
	v_add_f32_e32 v92, v92, v140
	v_add_f32_e32 v93, v93, v141
	v_add_f32_e32 v88, v88, v136
	v_add_f32_e32 v89, v89, v137
	v_add_f32_e32 v82, v82, v130
	v_add_f32_e32 v83, v83, v131
	ds_read_b128 v[130:133], v162 offset:128
	ds_read_b128 v[134:137], v162 offset:144
	ds_read_b128 v[138:141], v162 offset:192
	ds_read_b128 v[142:145], v162 offset:208
	s_waitcnt lgkmcnt(0)
	v_add_f32_e32 v100, v100, v132
	v_add_f32_e32 v101, v101, v133
	v_add_f32_e32 v102, v102, v134
	v_add_f32_e32 v103, v103, v135
	v_add_f32_e32 v106, v106, v138
	v_add_f32_e32 v107, v107, v139
	v_add_f32_e32 v110, v110, v142
	v_add_f32_e32 v111, v111, v143
	v_add_f32_e32 v112, v112, v144
	v_add_f32_e32 v113, v113, v145
	v_add_f32_e32 v108, v108, v140
	v_add_f32_e32 v109, v109, v141
	v_add_f32_e32 v104, v104, v136
	v_add_f32_e32 v105, v105, v137
	v_add_f32_e32 v98, v98, v130
	v_add_f32_e32 v99, v99, v131
	s_branch .LBB0_331
